# code placement: both merged GEMM K-loop heads aligned to 64 bytes
# speedup vs baseline: 1.0037x; 1.0037x over previous
.LBB0_387:
	v_mov_b32_e32 v0, 0
	s_mov_b32 s86, 0
	s_movk_i32 s85, 0x80
	v_mov_b32_e32 v1, v0
	v_mov_b32_e32 v2, v0
	v_mov_b32_e32 v3, v0
	v_mov_b32_e32 v4, v0
	v_mov_b32_e32 v5, v0
	v_mov_b32_e32 v6, v0
	v_mov_b32_e32 v7, v0
	v_mov_b32_e32 v8, v0
	v_mov_b32_e32 v9, v0
	v_mov_b32_e32 v10, v0
	v_mov_b32_e32 v11, v0
	v_mov_b32_e32 v12, v0
	v_mov_b32_e32 v13, v0
	v_mov_b32_e32 v14, v0
	v_mov_b32_e32 v15, v0
	v_mov_b32_e32 v16, v0
	v_mov_b32_e32 v17, v0
	v_mov_b32_e32 v18, v0
	v_mov_b32_e32 v19, v0
	v_mov_b32_e32 v28, v0
	v_mov_b32_e32 v29, v0
	v_mov_b32_e32 v30, v0
	v_mov_b32_e32 v31, v0
	v_mov_b32_e32 v32, v0
	v_mov_b32_e32 v33, v0
	v_mov_b32_e32 v34, v0
	v_mov_b32_e32 v35, v0
	v_mov_b32_e32 v44, v0
	v_mov_b32_e32 v45, v0
	v_mov_b32_e32 v46, v0
	v_mov_b32_e32 v47, v0
	v_mov_b32_e32 v20, v0
	v_mov_b32_e32 v21, v0
	v_mov_b32_e32 v22, v0
	v_mov_b32_e32 v23, v0
	v_mov_b32_e32 v24, v0
	v_mov_b32_e32 v25, v0
	v_mov_b32_e32 v26, v0
	v_mov_b32_e32 v27, v0
	v_mov_b32_e32 v36, v0
	v_mov_b32_e32 v37, v0
	v_mov_b32_e32 v38, v0
	v_mov_b32_e32 v39, v0
	v_mov_b32_e32 v40, v0
	v_mov_b32_e32 v41, v0
	v_mov_b32_e32 v42, v0
	v_mov_b32_e32 v43, v0
	v_mov_b32_e32 v48, v0
	v_mov_b32_e32 v49, v0
	v_mov_b32_e32 v50, v0
	v_mov_b32_e32 v51, v0
	v_mov_b32_e32 v52, v0
	v_mov_b32_e32 v53, v0
	v_mov_b32_e32 v54, v0
	v_mov_b32_e32 v55, v0
	v_mov_b32_e32 v56, v0
	v_mov_b32_e32 v57, v0
	v_mov_b32_e32 v58, v0
	v_mov_b32_e32 v59, v0
	v_mov_b32_e32 v60, v0
	v_mov_b32_e32 v61, v0
	v_mov_b32_e32 v62, v0
	v_mov_b32_e32 v63, v0
	v_mov_b32_e32 v64, v0
	v_mov_b32_e32 v65, v0
	v_mov_b32_e32 v66, v0
	v_mov_b32_e32 v67, v0
	v_mov_b32_e32 v68, v0
	v_mov_b32_e32 v69, v0
	v_mov_b32_e32 v70, v0
	v_mov_b32_e32 v71, v0
	v_mov_b32_e32 v72, v0
	v_mov_b32_e32 v73, v0
	v_mov_b32_e32 v74, v0
	v_mov_b32_e32 v75, v0
	v_mov_b32_e32 v76, v0
	v_mov_b32_e32 v77, v0
	v_mov_b32_e32 v78, v0
	v_mov_b32_e32 v79, v0
	v_mov_b32_e32 v84, v0
	v_mov_b32_e32 v85, v0
	v_mov_b32_e32 v86, v0
	v_mov_b32_e32 v87, v0
	v_mov_b32_e32 v92, v0
	v_mov_b32_e32 v93, v0
	v_mov_b32_e32 v94, v0
	v_mov_b32_e32 v95, v0
	v_mov_b32_e32 v100, v0
	v_mov_b32_e32 v101, v0
	v_mov_b32_e32 v102, v0
	v_mov_b32_e32 v103, v0
	v_mov_b32_e32 v116, v0
	v_mov_b32_e32 v117, v0
	v_mov_b32_e32 v118, v0
	v_mov_b32_e32 v119, v0
	v_mov_b32_e32 v80, v0
	v_mov_b32_e32 v81, v0
	v_mov_b32_e32 v82, v0
	v_mov_b32_e32 v83, v0
	v_mov_b32_e32 v88, v0
	v_mov_b32_e32 v89, v0
	v_mov_b32_e32 v90, v0
	v_mov_b32_e32 v91, v0
	v_mov_b32_e32 v96, v0
	v_mov_b32_e32 v97, v0
	v_mov_b32_e32 v98, v0
	v_mov_b32_e32 v99, v0
	v_mov_b32_e32 v104, v0
	v_mov_b32_e32 v105, v0
	v_mov_b32_e32 v106, v0
	v_mov_b32_e32 v107, v0
	v_mov_b32_e32 v108, v0
	v_mov_b32_e32 v109, v0
	v_mov_b32_e32 v110, v0
	v_mov_b32_e32 v111, v0
	v_mov_b32_e32 v112, v0
	v_mov_b32_e32 v113, v0
	v_mov_b32_e32 v114, v0
	v_mov_b32_e32 v115, v0
	v_mov_b32_e32 v120, v0
	v_mov_b32_e32 v121, v0
	v_mov_b32_e32 v122, v0
	v_mov_b32_e32 v123, v0
	v_mov_b32_e32 v124, v0
	v_mov_b32_e32 v125, v0
	v_mov_b32_e32 v126, v0
	v_mov_b32_e32 v127, v0
	.p2align	6

.LBB0_493:
	v_mov_b32_e32 v0, 0
	s_mov_b32 s86, 0
	s_movk_i32 s85, 0x80
	v_mov_b32_e32 v1, v0
	v_mov_b32_e32 v2, v0
	v_mov_b32_e32 v3, v0
	v_mov_b32_e32 v4, v0
	v_mov_b32_e32 v5, v0
	v_mov_b32_e32 v6, v0
	v_mov_b32_e32 v7, v0
	v_mov_b32_e32 v8, v0
	v_mov_b32_e32 v9, v0
	v_mov_b32_e32 v10, v0
	v_mov_b32_e32 v11, v0
	v_mov_b32_e32 v16, v0
	v_mov_b32_e32 v17, v0
	v_mov_b32_e32 v18, v0
	v_mov_b32_e32 v19, v0
	v_mov_b32_e32 v24, v0
	v_mov_b32_e32 v25, v0
	v_mov_b32_e32 v26, v0
	v_mov_b32_e32 v27, v0
	v_mov_b32_e32 v32, v0
	v_mov_b32_e32 v33, v0
	v_mov_b32_e32 v34, v0
	v_mov_b32_e32 v35, v0
	v_mov_b32_e32 v40, v0
	v_mov_b32_e32 v41, v0
	v_mov_b32_e32 v42, v0
	v_mov_b32_e32 v43, v0
	v_mov_b32_e32 v48, v0
	v_mov_b32_e32 v49, v0
	v_mov_b32_e32 v50, v0
	v_mov_b32_e32 v51, v0
	v_mov_b32_e32 v12, v0
	v_mov_b32_e32 v13, v0
	v_mov_b32_e32 v14, v0
	v_mov_b32_e32 v15, v0
	v_mov_b32_e32 v20, v0
	v_mov_b32_e32 v21, v0
	v_mov_b32_e32 v22, v0
	v_mov_b32_e32 v23, v0
	v_mov_b32_e32 v28, v0
	v_mov_b32_e32 v29, v0
	v_mov_b32_e32 v30, v0
	v_mov_b32_e32 v31, v0
	v_mov_b32_e32 v36, v0
	v_mov_b32_e32 v37, v0
	v_mov_b32_e32 v38, v0
	v_mov_b32_e32 v39, v0
	v_mov_b32_e32 v44, v0
	v_mov_b32_e32 v45, v0
	v_mov_b32_e32 v46, v0
	v_mov_b32_e32 v47, v0
	v_mov_b32_e32 v52, v0
	v_mov_b32_e32 v53, v0
	v_mov_b32_e32 v54, v0
	v_mov_b32_e32 v55, v0
	v_mov_b32_e32 v56, v0
	v_mov_b32_e32 v57, v0
	v_mov_b32_e32 v58, v0
	v_mov_b32_e32 v59, v0
	v_mov_b32_e32 v60, v0
	v_mov_b32_e32 v61, v0
	v_mov_b32_e32 v62, v0
	v_mov_b32_e32 v63, v0
	v_mov_b32_e32 v64, v0
	v_mov_b32_e32 v65, v0
	v_mov_b32_e32 v66, v0
	v_mov_b32_e32 v67, v0
	v_mov_b32_e32 v68, v0
	v_mov_b32_e32 v69, v0
	v_mov_b32_e32 v70, v0
	v_mov_b32_e32 v71, v0
	v_mov_b32_e32 v72, v0
	v_mov_b32_e32 v73, v0
	v_mov_b32_e32 v74, v0
	v_mov_b32_e32 v75, v0
	v_mov_b32_e32 v80, v0
	v_mov_b32_e32 v81, v0
	v_mov_b32_e32 v82, v0
	v_mov_b32_e32 v83, v0
	v_mov_b32_e32 v88, v0
	v_mov_b32_e32 v89, v0
	v_mov_b32_e32 v90, v0
	v_mov_b32_e32 v91, v0
	v_mov_b32_e32 v96, v0
	v_mov_b32_e32 v97, v0
	v_mov_b32_e32 v98, v0
	v_mov_b32_e32 v99, v0
	v_mov_b32_e32 v104, v0
	v_mov_b32_e32 v105, v0
	v_mov_b32_e32 v106, v0
	v_mov_b32_e32 v107, v0
	v_mov_b32_e32 v112, v0
	v_mov_b32_e32 v113, v0
	v_mov_b32_e32 v114, v0
	v_mov_b32_e32 v115, v0
	v_mov_b32_e32 v76, v0
	v_mov_b32_e32 v77, v0
	v_mov_b32_e32 v78, v0
	v_mov_b32_e32 v79, v0
	v_mov_b32_e32 v84, v0
	v_mov_b32_e32 v85, v0
	v_mov_b32_e32 v86, v0
	v_mov_b32_e32 v87, v0
	v_mov_b32_e32 v92, v0
	v_mov_b32_e32 v93, v0
	v_mov_b32_e32 v94, v0
	v_mov_b32_e32 v95, v0
	v_mov_b32_e32 v100, v0
	v_mov_b32_e32 v101, v0
	v_mov_b32_e32 v102, v0
	v_mov_b32_e32 v103, v0
	v_mov_b32_e32 v108, v0
	v_mov_b32_e32 v109, v0
	v_mov_b32_e32 v110, v0
	v_mov_b32_e32 v111, v0
	v_mov_b32_e32 v116, v0
	v_mov_b32_e32 v117, v0
	v_mov_b32_e32 v118, v0
	v_mov_b32_e32 v119, v0
	v_mov_b32_e32 v120, v0
	v_mov_b32_e32 v121, v0
	v_mov_b32_e32 v122, v0
	v_mov_b32_e32 v123, v0
	v_mov_b32_e32 v124, v0
	v_mov_b32_e32 v125, v0
	v_mov_b32_e32 v126, v0
	v_mov_b32_e32 v127, v0
	.p2align	6
